# nt hint also on the layer-0 f32 input row reads of the norm phases
# baseline (speedup 1.0000x reference)
.LBB0_149:
	s_add_i32 s46, s6, 0xffffe000
	s_cmpk_gt_i32 s6, 0x1fff
	s_cselect_b64 s[4:5], -1, 0
	s_and_b64 s[12:13], s[4:5], exec
	v_readlane_b32 s14, v254, 46
	s_cselect_b32 s12, s46, s6
	v_readlane_b32 s15, v254, 47
	s_cselect_b32 s7, s3, s1
	s_cselect_b32 s18, s2, s0
	s_ashr_i32 s13, s12, 31
	s_and_b64 vcc, exec, s[14:15]
	s_mov_b64 s[14:15], -1
	s_cbranch_vccnz .LBB0_151
	s_lshl_b64 s[14:15], s[12:13], 13
	s_add_u32 s14, s18, s14
	s_addc_u32 s15, s7, s15
	v_lshl_add_u64 v[2:3], s[14:15], 0, v[0:1]
	global_load_dwordx4 v[26:29], v0, s[14:15] offset:16 nt
	global_load_dwordx4 v[30:33], v0, s[14:15] nt
	global_load_dwordx4 v[18:21], v0, s[14:15] offset:2064 nt
	global_load_dwordx4 v[22:25], v0, s[14:15] offset:2048 nt
	s_mov_b64 s[14:15], 0x1000
	v_lshl_add_u64 v[4:5], v[2:3], 0, s[14:15]
	s_movk_i32 s14, 0x1000
	v_add_co_u32_e32 v6, vcc, s14, v2
	s_mov_b64 s[14:15], 0x1800
	s_nop 0
	v_addc_co_u32_e32 v7, vcc, 0, v3, vcc
	v_lshl_add_u64 v[2:3], v[2:3], 0, s[14:15]
	global_load_dwordx4 v[14:17], v[6:7], off nt
	global_load_dwordx4 v[10:13], v[4:5], off offset:16 nt
	s_nop 0
	global_load_dwordx4 v[6:9], v[6:7], off offset:2048 nt
	s_nop 0
	global_load_dwordx4 v[2:5], v[2:3], off offset:16 nt
	s_mov_b64 s[14:15], 0

.LBB0_1030:
	s_cmpk_gt_i32 s2, 0x1fff
	s_cselect_b64 s[10:11], -1, 0
	s_add_i32 s46, s2, 0xffffe000
	s_cmpk_lt_i32 s2, 0x2000
	s_cselect_b64 s[4:5], -1, 0
	v_readlane_b32 s12, v254, 44
	s_and_b64 s[8:9], s[4:5], exec
	v_readlane_b32 s13, v254, 45
	s_cselect_b32 s8, s2, s46
	s_or_b64 s[18:19], s[12:13], s[4:5]
	s_ashr_i32 s9, s8, 31
	s_mov_b64 s[12:13], -1
	s_and_b64 vcc, exec, s[18:19]
	s_cbranch_vccnz .LBB0_1032
	s_lshl_b64 s[12:13], s[8:9], 13
	v_lshl_add_u64 v[2:3], v[138:139], 0, s[12:13]
	s_mov_b64 s[12:13], 0x1000
	global_load_dwordx4 v[26:29], v[2:3], off offset:16 nt
	global_load_dwordx4 v[30:33], v[2:3], off nt
	global_load_dwordx4 v[18:21], v[2:3], off offset:2064 nt
	global_load_dwordx4 v[22:25], v[2:3], off offset:2048 nt
	v_lshl_add_u64 v[4:5], v[2:3], 0, s[12:13]
	v_add_co_u32_e32 v6, vcc, 0x1000, v2
	s_mov_b64 s[12:13], 0x1800
	s_nop 0
	v_addc_co_u32_e32 v7, vcc, 0, v3, vcc
	v_lshl_add_u64 v[2:3], v[2:3], 0, s[12:13]
	global_load_dwordx4 v[14:17], v[6:7], off nt
	global_load_dwordx4 v[10:13], v[4:5], off offset:16 nt
	s_nop 0
	global_load_dwordx4 v[6:9], v[6:7], off offset:2048 nt
	s_nop 0
	global_load_dwordx4 v[2:5], v[2:3], off offset:16 nt
	s_mov_b64 s[12:13], 0
